# v66: acquire invalidate issued right after the workgroup's arrival atomic returns, so its ~1.7us latency overlaps the barrier wait (no cacheable loads happen between arrival and release)
# speedup vs baseline: 1.0176x; 1.0132x over previous
; __device__ __forceinline__ unsigned xb_ld(unsigned* p)              { return __hip_atomic_load(p, __ATOMIC_RELAXED, __HIP_MEMORY_SCOPE_AGENT); }
; __device__ __forceinline__ unsigned xb_add(unsigned* p, unsigned v) { return __hip_atomic_fetch_add(p, v, __ATOMIC_RELAXED, __HIP_MEMORY_SCOPE_AGENT); }
; #define XB_SPIN(cond, bar) do { unsigned _sp = 0; while (cond) { __builtin_amdgcn_s_sleep(1); \
;     if ((++_sp & 255u) == 0u) { if (xb_ld(&(bar)[XB_TMO])) break; if (_sp > XB_SPIN_CAP) { atomicAdd(&(bar)[XB_TMO], 1u); break; } } } } while (0)
; __device__ __forceinline__ void xcd_barrier(const XcdBarrier& b) {
;     ...
;     if (threadIdx.x == 0) {
;         unsigned* bar = b.bar;
;         __builtin_amdgcn_s_waitcnt(0);
;         unsigned nloc = b.st[0], nx = b.st[1];
;         if (nloc == 0u) { xcd_barrier_complete(bar, b.x, nloc, nx); b.st[0] = nloc; b.st[1] = nx; }
;         const unsigned old = xb_add(&bar[XB_XSUB(b.x)], 1u);
;         const unsigned gen = old / nloc;
;         if (old + 1u == (gen + 1u) * nloc) {
;             __builtin_amdgcn_fence(__ATOMIC_RELEASE, "agent");
;             asm volatile("s_waitcnt vmcnt(0)" ::: "memory");
;             const unsigned og = xb_add(&bar[XB_TOP], 1u);
;             const unsigned tg = og / nx;
;             if (og + 1u == (tg + 1u) * nx) xb_add(&bar[XB_TOPGEN], 1u);
;             else XB_SPIN(xb_ld(&bar[XB_TOPGEN]) == tg, bar);
;             __builtin_amdgcn_fence(__ATOMIC_ACQUIRE, "agent");
;             xb_add(&bar[XB_XGEN(b.x)], 1u);
;             asm volatile("s_waitcnt vmcnt(0)" ::: "memory");
;         } else {
;             XB_SPIN(xb_ld(&bar[XB_XGEN(b.x)]) == gen, bar);
;             __builtin_amdgcn_fence(__ATOMIC_ACQUIRE, "agent");
;             asm volatile("s_waitcnt vmcnt(0)" ::: "memory");
;         }
.LBB0_82:
	v_mov_b32_e32 v4, 0x20000
	ds_read2_b32 v[2:3], v4 offset1:1
	v_readlane_b32 s3, v244, 30
	s_nop 0
	s_lshl_b32 s3, s3, 8
	s_getpc_b64 s[4:5]
	s_add_u32 s4, s4, g_xbar@rel32@lo+4
	s_addc_u32 s5, s5, g_xbar@rel32@hi+12
	s_add_u32 s4, s4, s3
	s_addc_u32 s5, s5, 0
	v_mov_b32_e32 v5, 0x1000
	v_mov_b32_e32 v6, 1
	global_atomic_add v5, v5, v6, s[4:5] offset:1024 sc0
	s_movk_i32 s3, 1
	s_waitcnt lgkmcnt(0)
	v_mul_lo_u32 v2, v2, s3
	v_mul_lo_u32 v3, v3, s3
	s_waitcnt vmcnt(0)
	buffer_inv sc1
	v_add_u32_e32 v5, 1, v5
	v_cmp_ne_u32_e32 vcc, v5, v2
	s_getpc_b64 s[4:5]
	s_add_u32 s4, s4, g_xbar@rel32@lo+13316
	s_addc_u32 s5, s5, g_xbar@rel32@hi+13324
	v_mov_b32_e32 v4, 0
	s_cbranch_vccnz .Lfb0_spin0
	buffer_wbl2 sc1
	s_waitcnt vmcnt(0) lgkmcnt(0)
	global_atomic_add v4, v6, s[4:5]

; __device__ __forceinline__ unsigned xb_ld(unsigned* p)              { return __hip_atomic_load(p, __ATOMIC_RELAXED, __HIP_MEMORY_SCOPE_AGENT); }
; __device__ __forceinline__ unsigned xb_add(unsigned* p, unsigned v) { return __hip_atomic_fetch_add(p, v, __ATOMIC_RELAXED, __HIP_MEMORY_SCOPE_AGENT); }
; #define XB_SPIN(cond, bar) do { unsigned _sp = 0; while (cond) { __builtin_amdgcn_s_sleep(1); \
;     if ((++_sp & 255u) == 0u) { if (xb_ld(&(bar)[XB_TMO])) break; if (_sp > XB_SPIN_CAP) { atomicAdd(&(bar)[XB_TMO], 1u); break; } } } } while (0)
;     __device__ __forceinline__ bool next(int i, int& pm, int& pn, int& k0, int& nk, int& slice, int& src) const {
;         const long L = (long)i * G + c;
;         pm = 0; pn = 0; k0 = 0; nk = nt; slice = -1; src = 0;
;         if (L < nwg) {
;             int wgid = (int)L; { const int q = nwg / NXCD, r = nwg % NXCD, xcd = wgid % NXCD, off = wgid / NXCD; wgid = (xcd < r ? xcd * (q + 1) : r * (q + 1) + (xcd - r) * q) + off; }
;             const int nig = WGM * nN, gid = wgid / nig, fm = gid * WGM, gsz = (nM - fm) < WGM ? (nM - fm) : WGM;
;             pm = fm + ((wgid % nig) % gsz); pn = (wgid % nig) / gsz; return true;
; __device__ __forceinline__ void xcd_barrier(const XcdBarrier& b) {
;     ...
;             const unsigned tg = og / nx;
;             if (og + 1u == (tg + 1u) * nx) xb_add(&bar[XB_TOPGEN], 1u);
;             else XB_SPIN(xb_ld(&bar[XB_TOPGEN]) == tg, bar);
;             __builtin_amdgcn_fence(__ATOMIC_ACQUIRE, "agent");
;             xb_add(&bar[XB_XGEN(b.x)], 1u);
;             asm volatile("s_waitcnt vmcnt(0)" ::: "memory");
;         } else {
;             XB_SPIN(xb_ld(&bar[XB_XGEN(b.x)]) == gen, bar);
;             __builtin_amdgcn_fence(__ATOMIC_ACQUIRE, "agent");
;             asm volatile("s_waitcnt vmcnt(0)" ::: "memory");
;         }
;     }
;     __syncthreads();
.Lfb0_spin:
	global_load_dword v5, v4, s[4:5] sc1
	s_waitcnt vmcnt(0)
	v_cmp_ge_u32_e32 vcc, v5, v3
	s_cbranch_vccnz .Lfb0_done
	s_sleep 1
	s_add_u32 s3, s3, 1
	s_cmp_lt_u32 s3, 0x200000
	s_cbranch_scc1 .Lfb0_spin
.Lfb0_done:
	s_waitcnt vmcnt(0)
.LBB0_118:
	s_or_b64 exec, exec, s[0:1]
	v_readlane_b32 s3, v244, 33
	v_mov_b32_e32 v10, v0
	s_cmpk_lt_i32 s3, 0x35a
	s_waitcnt lgkmcnt(0)
	s_barrier
	s_mov_b32 s4, 0
	v_readfirstlane_b32 s12, v10
	s_cselect_b64 s[0:1], -1, 0
	s_cmpk_gt_i32 s3, 0x359
	s_mov_b32 s6, 0
	s_cbranch_scc1 .LBB0_124
	v_readlane_b32 s5, v244, 33
	s_ashr_i32 s3, s5, 31
	s_lshr_b32 s3, s3, 29
	s_add_i32 s3, s5, s3
	s_and_b32 s4, s3, -8
	s_sub_i32 s6, s5, s4
	s_cmp_gt_i32 s6, 1
	s_cbranch_scc0 .LBB0_121
	s_mul_i32 s4, s6, 0x6b
	s_add_i32 s7, s4, 2
	s_cbranch_execz .LBB0_122
	s_branch .LBB0_123

; __device__ __forceinline__ unsigned xb_ld(unsigned* p)              { return __hip_atomic_load(p, __ATOMIC_RELAXED, __HIP_MEMORY_SCOPE_AGENT); }
; __device__ __forceinline__ unsigned xb_add(unsigned* p, unsigned v) { return __hip_atomic_fetch_add(p, v, __ATOMIC_RELAXED, __HIP_MEMORY_SCOPE_AGENT); }
; #define XB_SPIN(cond, bar) do { unsigned _sp = 0; while (cond) { __builtin_amdgcn_s_sleep(1); \
;     if ((++_sp & 255u) == 0u) { if (xb_ld(&(bar)[XB_TMO])) break; if (_sp > XB_SPIN_CAP) { atomicAdd(&(bar)[XB_TMO], 1u); break; } } } } while (0)
; __device__ __forceinline__ void xcd_barrier(const XcdBarrier& b) {
;     ...
;     if (threadIdx.x == 0) {
;         unsigned* bar = b.bar;
;         __builtin_amdgcn_s_waitcnt(0);
;         unsigned nloc = b.st[0], nx = b.st[1];
;         if (nloc == 0u) { xcd_barrier_complete(bar, b.x, nloc, nx); b.st[0] = nloc; b.st[1] = nx; }
;         const unsigned old = xb_add(&bar[XB_XSUB(b.x)], 1u);
;         const unsigned gen = old / nloc;
;         if (old + 1u == (gen + 1u) * nloc) {
;             __builtin_amdgcn_fence(__ATOMIC_RELEASE, "agent");
;             asm volatile("s_waitcnt vmcnt(0)" ::: "memory");
;             const unsigned og = xb_add(&bar[XB_TOP], 1u);
;             const unsigned tg = og / nx;
;             if (og + 1u == (tg + 1u) * nx) xb_add(&bar[XB_TOPGEN], 1u);
;             else XB_SPIN(xb_ld(&bar[XB_TOPGEN]) == tg, bar);
;             __builtin_amdgcn_fence(__ATOMIC_ACQUIRE, "agent");
;             xb_add(&bar[XB_XGEN(b.x)], 1u);
;             asm volatile("s_waitcnt vmcnt(0)" ::: "memory");
;         } else {
;             XB_SPIN(xb_ld(&bar[XB_XGEN(b.x)]) == gen, bar);
;             __builtin_amdgcn_fence(__ATOMIC_ACQUIRE, "agent");
;             asm volatile("s_waitcnt vmcnt(0)" ::: "memory");
;         }
.LBB0_464:
	v_mov_b32_e32 v4, 0x20000
	ds_read2_b32 v[2:3], v4 offset1:1
	v_readlane_b32 s3, v244, 30
	s_nop 0
	s_lshl_b32 s3, s3, 8
	s_getpc_b64 s[4:5]
	s_add_u32 s4, s4, g_xbar@rel32@lo+4
	s_addc_u32 s5, s5, g_xbar@rel32@hi+12
	s_add_u32 s4, s4, s3
	s_addc_u32 s5, s5, 0
	v_mov_b32_e32 v5, 0x1000
	v_mov_b32_e32 v6, 1
	global_atomic_add v5, v5, v6, s[4:5] offset:1024 sc0
	s_movk_i32 s3, 2
	s_waitcnt lgkmcnt(0)
	v_mul_lo_u32 v2, v2, s3
	v_mul_lo_u32 v3, v3, s3
	s_waitcnt vmcnt(0)
	buffer_inv sc1
	v_add_u32_e32 v5, 1, v5
	v_cmp_ne_u32_e32 vcc, v5, v2
	s_getpc_b64 s[4:5]
	s_add_u32 s4, s4, g_xbar@rel32@lo+13316
	s_addc_u32 s5, s5, g_xbar@rel32@hi+13324
	v_mov_b32_e32 v4, 0
	s_cbranch_vccnz .Lfb1_spin0
	buffer_wbl2 sc1
	s_waitcnt vmcnt(0) lgkmcnt(0)
	global_atomic_add v4, v6, s[4:5]

; __device__ __forceinline__ unsigned xb_ld(unsigned* p)              { return __hip_atomic_load(p, __ATOMIC_RELAXED, __HIP_MEMORY_SCOPE_AGENT); }
; __device__ __forceinline__ void attn_block_unit(const Params& p, int bu, char* lds, int tid) {
;   const int b = bu >> 5, kv = (bu >> 4) & 1, blk = bu & 15, lane = tid & 63, wid = tid >> 6;
;   const bf16_t* Kp = (const bf16_t*)(p.ws + OFF_KP); const bf16_t* Vtp = (const bf16_t*)(p.ws + OFF_VTP);
;   char* K_l = lds; char* Vt_l = lds + ATT_VOFF;
;   u32x4 kr[4], vr[4];
; #pragma unroll
;   for (int i = 0; i < 4; ++i) {
;     const int piece = tid + i * NTHR, key = piece >> 3, c = piece & 7;
;     if (blk > 0 || key >= 128) kr[i] = *(const u32x4*)(Kp + ((size_t)b * 2048 + (size_t)(blk - 1) * 128 + key) * 128 + kv * 64 + c * 8);
;     const int d = piece >> 5, c2 = piece & 31;
;     if (blk > 0 || c2 >= 16) vr[i] = *(const u32x4*)(Vtp + ((size_t)(b * 2 + kv) * 64 + d) * 2048 + (size_t)(blk - 1) * 128 + c2 * 8);
;   }
; #pragma unroll
;   for (int i = 0; i < 4; ++i) {
;     const int piece = tid + i * NTHR, key = piece >> 3, c = piece & 7;
;     if (blk > 0 || key >= 128) *(u32x4*)(K_l + key * ATT_KSTR + c * 16) = kr[i];
;     const int d = piece >> 5, c2 = piece & 31;
;     if (blk > 0 || c2 >= 16) *(u32x4*)(Vt_l + d * ATT_VSTR + c2 * 16) = vr[i];
;   }
;   __syncthreads();
;   const int pl = lane & 15;
; #pragma unroll 1
;   for (int g = 0; g < 4; ++g) {
;     asm volatile("" ::: "memory");
;     attn_core<true>(p, lane, K_l, ATT_KSTR, Vt_l, ATT_VSTR, wid, blk > 0, b * 2048 + blk * 128 + wid * 16 + pl, kv * 4 + g, wid * 16 + pl);
; __device__ __forceinline__ void xcd_barrier(const XcdBarrier& b) {
;     ...
;             const unsigned tg = og / nx;
;             if (og + 1u == (tg + 1u) * nx) xb_add(&bar[XB_TOPGEN], 1u);
;             else XB_SPIN(xb_ld(&bar[XB_TOPGEN]) == tg, bar);
;             __builtin_amdgcn_fence(__ATOMIC_ACQUIRE, "agent");
;             xb_add(&bar[XB_XGEN(b.x)], 1u);
;             asm volatile("s_waitcnt vmcnt(0)" ::: "memory");
;         } else {
;             XB_SPIN(xb_ld(&bar[XB_XGEN(b.x)]) == gen, bar);
;             __builtin_amdgcn_fence(__ATOMIC_ACQUIRE, "agent");
;             asm volatile("s_waitcnt vmcnt(0)" ::: "memory");
;         }
;     }
;     __syncthreads();
.Lfb1_spin:
	global_load_dword v5, v4, s[4:5] sc1
	s_waitcnt vmcnt(0)
	v_cmp_ge_u32_e32 vcc, v5, v3
	s_cbranch_vccnz .Lfb1_done
	s_sleep 1
	s_add_u32 s3, s3, 1
	s_cmp_lt_u32 s3, 0x200000
	s_cbranch_scc1 .Lfb1_spin
.Lfb1_done:
	s_waitcnt vmcnt(0)
.LBB0_500:
	s_or_b64 exec, exec, s[0:1]
	v_readlane_b32 s0, v244, 33
	s_cmpk_lt_i32 s0, 0x100
	s_cselect_b64 s[4:5], -1, 0
	v_writelane_b32 v244, s4, 60
	s_cmpk_gt_i32 s0, 0xff
	s_cselect_b64 s[0:1], -1, 0
	v_writelane_b32 v244, s5, 61
	v_writelane_b32 v244, s0, 62
	s_and_b64 vcc, exec, s[0:1]
	v_and_b32_e32 v78, 15, v0
	v_lshrrev_b32_e32 v79, 4, v184
	v_and_b32_e32 v82, 48, v0
	v_or_b32_e32 v80, 48, v184
	v_mbcnt_lo_u32_b32 v185, -1, 0
	s_waitcnt lgkmcnt(0)
	s_barrier
	v_writelane_b32 v244, s1, 63
	s_cbranch_vccnz .LBB0_529
	v_readlane_b32 s8, v244, 0
	v_lshlrev_b32_e32 v2, 4, v0
	v_mov_b32_e32 v6, 0
	v_readlane_b32 s10, v244, 2
	v_readlane_b32 s11, v244, 3
	v_and_b32_e32 v2, 0x70, v2
	v_mov_b32_e32 v3, v6
	v_lshl_add_u64 v[4:5], s[10:11], 0, v[2:3]
	v_lshlrev_b32_e32 v3, 6, v0
	s_mov_b64 s[4:5], 0xa500000
	v_and_b32_e32 v8, 0x7800, v3
	v_or_b32_e32 v3, 0x200, v0
	v_lshl_add_u64 v[84:85], v[4:5], 0, s[4:5]
	v_lshlrev_b32_e32 v5, 6, v3
	v_and_b32_e32 v10, 0xf800, v5
	v_or_b32_e32 v5, 0x400, v0
	v_lshlrev_b32_e32 v7, 6, v5
	v_lshlrev_b32_e32 v20, 4, v183
	v_add_u32_e32 v113, 1, v183
	v_lshlrev_b32_e32 v24, 2, v79
	v_and_b32_e32 v12, 0x17800, v7
	v_or_b32_e32 v7, 0x600, v0
	v_or_b32_e32 v81, v20, v78
	v_add_u32_e32 v115, 2, v183
	v_or_b32_e32 v128, v24, v20
	v_bitop3_b32 v129, v24, v20, v24 bitop3:3
	v_lshlrev_b32_e32 v20, 4, v113
	v_lshlrev_b32_e32 v9, 6, v7
	v_add_u32_e32 v117, 3, v183
	v_or_b32_e32 v130, v24, v20
	v_bitop3_b32 v131, v24, v20, v24 bitop3:3
	v_lshlrev_b32_e32 v20, 4, v115
	v_and_b32_e32 v14, 0x1f800, v9
	v_add_u32_e32 v9, 0, v2
	v_lshrrev_b32_e32 v2, 5, v0
	v_add_u32_e32 v119, 4, v183
	v_or_b32_e32 v132, v24, v20
	v_bitop3_b32 v133, v24, v20, v24 bitop3:3
	v_lshlrev_b32_e32 v20, 4, v117
	v_cmp_lt_u32_e64 s[0:1], 15, v135
	v_lshlrev_b32_e32 v4, 3, v135
	v_lshl_add_u32 v11, v135, 4, 0
	v_mul_u32_u24_e32 v15, 0x210, v2
	v_lshrrev_b32_e32 v2, 5, v3
	v_add_u32_e32 v121, 5, v183
	v_or_b32_e32 v135, v24, v20
	v_bitop3_b32 v136, v24, v20, v24 bitop3:3
	v_lshlrev_b32_e32 v20, 4, v119
	v_mul_u32_u24_e32 v18, 0x210, v2
	v_lshrrev_b32_e32 v2, 5, v5
	v_add_u32_e32 v123, 6, v183
	v_or_b32_e32 v137, v24, v20
	v_bitop3_b32 v138, v24, v20, v24 bitop3:3
	v_lshlrev_b32_e32 v20, 4, v121
	v_lshrrev_b32_e32 v88, 3, v5
	v_mul_u32_u24_e32 v5, 0x210, v2
	v_lshrrev_b32_e32 v2, 5, v7
	v_add_u32_e32 v125, 7, v183
	v_or_b32_e32 v21, 8, v183
	v_or_b32_e32 v139, v24, v20
	v_bitop3_b32 v140, v24, v20, v24 bitop3:3
	v_lshlrev_b32_e32 v20, 4, v123
	v_lshrrev_b32_e32 v90, 3, v7
	v_mul_u32_u24_e32 v7, 0x210, v2
	v_lshlrev_b32_e32 v2, 3, v79
	v_lshlrev_b32_e32 v22, 4, v21
	v_or_b32_e32 v141, v24, v20
	v_bitop3_b32 v142, v24, v20, v24 bitop3:3
	v_lshlrev_b32_e32 v20, 4, v125
	v_lshrrev_b32_e32 v86, 3, v3
	s_movk_i32 s6, 0x210
	v_mov_b32_e32 v3, v6
	v_or_b32_e32 v23, v22, v78
	v_or_b32_e32 v143, v24, v20
	v_bitop3_b32 v144, v24, v20, v24 bitop3:3
	v_add_u32_e32 v20, 0, v2
	s_add_u32 s3, s10, 0xa900000
	s_movk_i32 s4, 0x1ff
	v_mul_u32_u24_e32 v13, 0x90, v134
	v_mul_u32_u24_e32 v16, 0x90, v86
	v_mul_u32_u24_e32 v17, 0x90, v88
	v_mul_u32_u24_e32 v19, 0x90, v90
	v_add_u32_e32 v112, 0, v82
	v_mul_u32_u24_e32 v23, 0x90, v23
	v_mad_u32_u24 v147, v78, s6, v20
	v_mad_u32_u24 v148, v80, s6, v20
	v_mov_b32_e32 v83, v6
	v_lshl_add_u64 v[2:3], s[10:11], 0, v[2:3]
	s_mov_b64 s[6:7], 0x7380040
	v_readlane_b32 s83, v244, 33
	s_addc_u32 s81, s11, 0
	v_cmp_lt_u32_e64 s[4:5], s4, v0
	v_mov_b32_e32 v87, v6
	v_mov_b32_e32 v89, v6
	v_mov_b32_e32 v91, v6
	s_mov_b32 s85, 0
	v_max_u32_e32 v114, 8, v113
	v_max_u32_e32 v116, 8, v115
	v_max_u32_e32 v118, 8, v117
	v_max_u32_e32 v120, 8, v119
	v_max_u32_e32 v122, 8, v121
	v_max_u32_e32 v124, 8, v123
	v_max_u32_e32 v126, 8, v125
	v_mov_b32_e32 v127, 0x7f
	v_or_b32_e32 v145, v24, v22
	v_bitop3_b32 v146, v24, v22, v24 bitop3:3
	v_lshlrev_b32_e32 v149, 5, v21
	v_lshl_add_u64 v[92:93], s[10:11], 0, v[82:83]
	v_lshl_add_u64 v[94:95], v[2:3], 0, s[6:7]
	v_lshlrev_b32_e32 v96, 1, v4
	v_lshlrev_b32_e32 v98, 1, v8
	v_lshlrev_b32_e32 v100, 1, v10
	v_lshlrev_b32_e32 v102, 1, v12
	v_lshlrev_b32_e32 v104, 1, v14
	v_add_u32_e32 v83, v9, v13
	v_add_u32_e32 v150, v11, v15
	v_add_u32_e32 v151, v9, v16
	v_add_u32_e32 v152, v11, v18
	v_add_u32_e32 v153, v11, v5
	v_add_u32_e32 v154, v9, v19
	v_add_u32_e32 v155, v11, v7
	v_add_u32_e32 v156, v112, v23
	v_add_u32_e32 v157, v9, v17
	v_mov_b32_e32 v158, 0xff800000
	v_mbcnt_hi_u32_b32 v159, -1, v185
	s_mov_b32 s82, s83
	v_readlane_b32 s9, v244, 1

; __device__ __forceinline__ unsigned xb_ld(unsigned* p)              { return __hip_atomic_load(p, __ATOMIC_RELAXED, __HIP_MEMORY_SCOPE_AGENT); }
; __device__ __forceinline__ unsigned xb_add(unsigned* p, unsigned v) { return __hip_atomic_fetch_add(p, v, __ATOMIC_RELAXED, __HIP_MEMORY_SCOPE_AGENT); }
; #define XB_SPIN(cond, bar) do { unsigned _sp = 0; while (cond) { __builtin_amdgcn_s_sleep(1); \
;     if ((++_sp & 255u) == 0u) { if (xb_ld(&(bar)[XB_TMO])) break; if (_sp > XB_SPIN_CAP) { atomicAdd(&(bar)[XB_TMO], 1u); break; } } } } while (0)
; __device__ __forceinline__ void xcd_barrier(const XcdBarrier& b) {
;     ...
;     if (threadIdx.x == 0) {
;         unsigned* bar = b.bar;
;         __builtin_amdgcn_s_waitcnt(0);
;         unsigned nloc = b.st[0], nx = b.st[1];
;         if (nloc == 0u) { xcd_barrier_complete(bar, b.x, nloc, nx); b.st[0] = nloc; b.st[1] = nx; }
;         const unsigned old = xb_add(&bar[XB_XSUB(b.x)], 1u);
;         const unsigned gen = old / nloc;
;         if (old + 1u == (gen + 1u) * nloc) {
;             __builtin_amdgcn_fence(__ATOMIC_RELEASE, "agent");
;             asm volatile("s_waitcnt vmcnt(0)" ::: "memory");
;             const unsigned og = xb_add(&bar[XB_TOP], 1u);
;             const unsigned tg = og / nx;
;             if (og + 1u == (tg + 1u) * nx) xb_add(&bar[XB_TOPGEN], 1u);
;             else XB_SPIN(xb_ld(&bar[XB_TOPGEN]) == tg, bar);
;             __builtin_amdgcn_fence(__ATOMIC_ACQUIRE, "agent");
;             xb_add(&bar[XB_XGEN(b.x)], 1u);
;             asm volatile("s_waitcnt vmcnt(0)" ::: "memory");
;         } else {
;             XB_SPIN(xb_ld(&bar[XB_XGEN(b.x)]) == gen, bar);
;             __builtin_amdgcn_fence(__ATOMIC_ACQUIRE, "agent");
;             asm volatile("s_waitcnt vmcnt(0)" ::: "memory");
;         }
.LBB0_594:
	v_mov_b32_e32 v4, 0x20000
	ds_read2_b32 v[2:3], v4 offset1:1
	v_readlane_b32 s6, v244, 30
	s_nop 0
	s_lshl_b32 s6, s6, 8
	s_getpc_b64 s[4:5]
	s_add_u32 s4, s4, g_xbar@rel32@lo+4
	s_addc_u32 s5, s5, g_xbar@rel32@hi+12
	s_add_u32 s4, s4, s6
	s_addc_u32 s5, s5, 0
	v_mov_b32_e32 v5, 0x1000
	v_mov_b32_e32 v6, 1
	global_atomic_add v5, v5, v6, s[4:5] offset:1024 sc0
	s_movk_i32 s6, 3
	s_waitcnt lgkmcnt(0)
	v_mul_lo_u32 v2, v2, s6
	v_mul_lo_u32 v3, v3, s6
	s_waitcnt vmcnt(0)
	buffer_inv sc1
	v_add_u32_e32 v5, 1, v5
	v_cmp_ne_u32_e32 vcc, v5, v2
	s_getpc_b64 s[4:5]
	s_add_u32 s4, s4, g_xbar@rel32@lo+13316
	s_addc_u32 s5, s5, g_xbar@rel32@hi+13324
	v_mov_b32_e32 v4, 0
	s_cbranch_vccnz .Lfb2_spin0
	buffer_wbl2 sc1
	s_waitcnt vmcnt(0) lgkmcnt(0)
	global_atomic_add v4, v6, s[4:5]

; #define GSYNC() xcd_barrier(xb)
;     __device__ __forceinline__ bool next(int i, int& pm, int& pn, int& k0, int& nk, int& slice, int& src) const {
;     ...
;         if (nsplit == 0) return false;
;         int sidx = (int)(L - nwg);
;         if (sidx >= nslice_items) return false;
;         int ncol = nN;
;         if (glu && sidx >= 64) { sidx -= 64; src = 1; ncol = 4; }
;         const int tl = sidx / nsplit; slice = sidx - tl * nsplit; pm = 64 + tl / ncol; pn = tl % ncol; nk = nt / nsplit; k0 = slice * nk; return true;
; __global__ void __launch_bounds__(512) fwd_megakernel(Params p) {
;     ...
;   GSYNC();
;   gemm_phase<EPI_GLU>(p, (const bf16_t*)(ws + OFF_GY), (const bf16_t*)(ws + OFF_WGLU), 512, 2048, glds, (const bf16_t*)(ws + OFF_O), (const bf16_t*)(ws + OFF_WATT));
.Lfb2_done:
	s_waitcnt vmcnt(0)
.LBB0_630:
	s_or_b64 exec, exec, s[0:1]
	v_readlane_b32 s4, v244, 0
	v_readlane_b32 s6, v244, 2
	v_readlane_b32 s7, v244, 3
	s_add_u32 s34, s6, 0x7380000
	s_addc_u32 s35, s7, 0
	s_add_u32 s36, s6, 0xce80000
	s_addc_u32 s37, s7, 0
	v_mov_b32_e32 v10, v0
	v_readlane_b32 s7, v244, 33
	s_waitcnt lgkmcnt(0)
	s_barrier
	s_cmpk_gt_i32 s7, 0x1ff
	v_readfirstlane_b32 s14, v10
	v_readlane_b32 s5, v244, 1
	s_cbranch_scc0 .LBB0_633
	s_cmpk_lt_u32 s7, 0x260
	s_mov_b64 s[12:13], 0
	s_cbranch_scc0 .LBB0_634
	s_cmpk_gt_u32 s7, 0x23f
	s_cselect_b64 s[0:1], -1, 0
	v_cndmask_b32_e64 v2, 0, 1, s[0:1]
	s_movk_i32 s4, 0xfdc0
	s_and_b64 s[0:1], s[0:1], exec
	s_cselect_b32 s0, s4, 0xfffffe00
	s_cselect_b32 s1, 2, 3
	s_cselect_b32 s5, 3, 7
	s_add_i32 s4, s0, s7
	s_lshr_b32 s6, s4, 2
	s_bfe_u32 s4, s4, 0x80002
	s_lshr_b32 s1, s4, s1
	s_and_b32 s0, s7, 3
	s_or_b32 s1, s1, 64
	v_readfirstlane_b32 s41, v2
	s_and_b32 s4, s1, 0x7f
	s_and_b32 s6, s6, s5
	s_lshl_b32 s8, s0, 8
	s_mov_b32 s9, 0
	s_mov_b64 s[10:11], -1
	s_mov_b32 s57, 2
	s_and_b64 vcc, exec, s[12:13]
	s_cbranch_vccnz .LBB0_635
	s_branch .LBB0_640

; __device__ __forceinline__ unsigned xb_ld(unsigned* p)              { return __hip_atomic_load(p, __ATOMIC_RELAXED, __HIP_MEMORY_SCOPE_AGENT); }
; __device__ __forceinline__ unsigned xb_add(unsigned* p, unsigned v) { return __hip_atomic_fetch_add(p, v, __ATOMIC_RELAXED, __HIP_MEMORY_SCOPE_AGENT); }
; #define XB_SPIN(cond, bar) do { unsigned _sp = 0; while (cond) { __builtin_amdgcn_s_sleep(1); \
;     if ((++_sp & 255u) == 0u) { if (xb_ld(&(bar)[XB_TMO])) break; if (_sp > XB_SPIN_CAP) { atomicAdd(&(bar)[XB_TMO], 1u); break; } } } } while (0)
; __device__ __forceinline__ void xcd_barrier(const XcdBarrier& b) {
;     ...
;     if (threadIdx.x == 0) {
;         unsigned* bar = b.bar;
;         __builtin_amdgcn_s_waitcnt(0);
;         unsigned nloc = b.st[0], nx = b.st[1];
;         if (nloc == 0u) { xcd_barrier_complete(bar, b.x, nloc, nx); b.st[0] = nloc; b.st[1] = nx; }
;         const unsigned old = xb_add(&bar[XB_XSUB(b.x)], 1u);
;         const unsigned gen = old / nloc;
;         if (old + 1u == (gen + 1u) * nloc) {
;             __builtin_amdgcn_fence(__ATOMIC_RELEASE, "agent");
;             asm volatile("s_waitcnt vmcnt(0)" ::: "memory");
;             const unsigned og = xb_add(&bar[XB_TOP], 1u);
;             const unsigned tg = og / nx;
;             if (og + 1u == (tg + 1u) * nx) xb_add(&bar[XB_TOPGEN], 1u);
;             else XB_SPIN(xb_ld(&bar[XB_TOPGEN]) == tg, bar);
;             __builtin_amdgcn_fence(__ATOMIC_ACQUIRE, "agent");
;             xb_add(&bar[XB_XGEN(b.x)], 1u);
;             asm volatile("s_waitcnt vmcnt(0)" ::: "memory");
;         } else {
;             XB_SPIN(xb_ld(&bar[XB_XGEN(b.x)]) == gen, bar);
;             __builtin_amdgcn_fence(__ATOMIC_ACQUIRE, "agent");
;             asm volatile("s_waitcnt vmcnt(0)" ::: "memory");
;         }
.LBB0_763:
	v_mov_b32_e32 v4, 0x20000
	ds_read2_b32 v[2:3], v4 offset1:1
	v_readlane_b32 s6, v244, 30
	s_nop 0
	s_lshl_b32 s6, s6, 8
	s_getpc_b64 s[4:5]
	s_add_u32 s4, s4, g_xbar@rel32@lo+4
	s_addc_u32 s5, s5, g_xbar@rel32@hi+12
	s_add_u32 s4, s4, s6
	s_addc_u32 s5, s5, 0
	v_mov_b32_e32 v5, 0x1000
	v_mov_b32_e32 v6, 1
	global_atomic_add v5, v5, v6, s[4:5] offset:1024 sc0
	s_movk_i32 s6, 5
	s_waitcnt lgkmcnt(0)
	v_mul_lo_u32 v2, v2, s6
	v_mul_lo_u32 v3, v3, s6
	s_waitcnt vmcnt(0)
	buffer_inv sc1
	v_add_u32_e32 v5, 1, v5
	v_cmp_ne_u32_e32 vcc, v5, v2
	s_getpc_b64 s[4:5]
	s_add_u32 s4, s4, g_xbar@rel32@lo+13316
	s_addc_u32 s5, s5, g_xbar@rel32@hi+13324
	v_mov_b32_e32 v4, 0
	s_cbranch_vccnz .Lfb4_spin0
	buffer_wbl2 sc1
	s_waitcnt vmcnt(0) lgkmcnt(0)
	global_atomic_add v4, v6, s[4:5]

;     __device__ __forceinline__ bool next(int i, int& pm, int& pn, int& k0, int& nk, int& slice, int& src) const {
;     ...
;         if (nsplit == 0) return false;
;         int sidx = (int)(L - nwg);
;         if (sidx >= nslice_items) return false;
;         int ncol = nN;
;         if (glu && sidx >= 64) { sidx -= 64; src = 1; ncol = 4; }
;         const int tl = sidx / nsplit; slice = sidx - tl * nsplit; pm = 64 + tl / ncol; pn = tl % ncol; nk = nt / nsplit; k0 = slice * nk; return true;
; __global__ void __launch_bounds__(512) fwd_megakernel(Params p) {
;     ...
;   gemm_phase<EPI_WO>(p, (const bf16_t*)(ws + OFF_MG), (const bf16_t*)(ws + OFF_WO), 1024, 1024, glds);
.Lfb4_done:
	s_waitcnt vmcnt(0)
.LBB0_799:
	s_or_b64 exec, exec, s[0:1]
	v_readlane_b32 s0, v244, 62
	v_mov_b32_e32 v10, v0
	v_readlane_b32 s1, v244, 63
	s_waitcnt lgkmcnt(0)
	s_barrier
	s_and_b64 vcc, exec, s[0:1]
	v_readfirstlane_b32 s14, v10
	s_cbranch_vccz .LBB0_802
	v_readlane_b32 s5, v244, 33
	s_cmpk_lt_u32 s5, 0x140
	s_mov_b64 s[12:13], 0
	s_cbranch_scc0 .LBB0_803
	s_add_i32 s1, s5, 0xffffff00
	s_and_b32 s0, s5, 7
	s_lshr_b32 s1, s1, 5
	s_add_i32 s4, s1, 64
	s_bfe_u32 s6, s5, 0x20003
	s_lshl_b32 s8, s0, 8
	s_mov_b32 s9, 0
	s_mov_b64 s[10:11], -1
	s_mov_b32 s52, 2
	s_and_b64 vcc, exec, s[12:13]
	s_cbranch_vccnz .LBB0_804
	s_branch .LBB0_809
